# v7 + grid barrier: non-leader workgroups spin on the cross-XCD release word (one hand-off less)
# baseline (speedup 1.0000x reference)
.LBB0_188:
	s_or_b64 exec, exec, s[12:13]
	v_cvt_f32_u32_e32 v4, v2
	s_waitcnt vmcnt(0)
	v_readfirstlane_b32 s2, v3
	v_sub_u32_e32 v3, 0, v2
	v_rcp_iflag_f32_e32 v4, v4
	v_add_u32_e32 v5, s2, v1
	v_mul_f32_e32 v4, 0x4f7ffffe, v4
	v_cvt_u32_f32_e32 v4, v4
	v_mul_lo_u32 v1, v3, v4
	v_mul_hi_u32 v1, v4, v1
	v_add_u32_e32 v1, v4, v1
	v_mul_hi_u32 v1, v5, v1
	v_mul_lo_u32 v3, v1, v2
	v_sub_u32_e32 v3, v5, v3
	v_add_u32_e32 v4, 1, v1
	v_cmp_ge_u32_e32 vcc, v3, v2
	s_nop 1
	v_cndmask_b32_e32 v1, v1, v4, vcc
	v_sub_u32_e32 v4, v3, v2
	v_cndmask_b32_e32 v3, v3, v4, vcc
	v_add_u32_e32 v4, 1, v1
	v_cmp_ge_u32_e32 vcc, v3, v2
	v_add_u32_e32 v3, 1, v5
	s_nop 0
	v_cndmask_b32_e32 v1, v1, v4, vcc
	v_mul_lo_u32 v4, v2, v1
	v_add_u32_e32 v2, v4, v2
	v_cmp_ne_u32_e32 vcc, v3, v2
	s_and_saveexec_b64 s[10:11], vcc
	s_xor_b64 s[10:11], exec, s[10:11]
	s_cbranch_execz .LBB0_202
	s_waitcnt lgkmcnt(0)
	v_mov_b32_e32 v0, 0
	s_add_u32 s16, s88, 0xeaf3500
	s_addc_u32 s17, s89, 0
	global_load_dword v0, v0, s[16:17] sc1
	s_waitcnt vmcnt(0)
	v_cmp_eq_u32_e32 vcc, v0, v1
	s_and_saveexec_b64 s[12:13], vcc
	s_cbranch_execz .LBB0_201
	s_add_u32 s14, s88, 0xeaf0200
	s_addc_u32 s15, s89, 0
	s_mov_b32 s2, 1
	s_mov_b64 s[20:21], 0
	v_mov_b32_e32 v0, 0
	s_branch .LBB0_192

.LBB0_406:
	s_or_b64 exec, exec, s[10:11]
	v_cvt_f32_u32_e32 v4, v2
	s_waitcnt vmcnt(0)
	v_readfirstlane_b32 s2, v3
	v_sub_u32_e32 v3, 0, v2
	v_rcp_iflag_f32_e32 v4, v4
	v_add_u32_e32 v5, s2, v1
	v_mul_f32_e32 v4, 0x4f7ffffe, v4
	v_cvt_u32_f32_e32 v4, v4
	v_mul_lo_u32 v1, v3, v4
	v_mul_hi_u32 v1, v4, v1
	v_add_u32_e32 v1, v4, v1
	v_mul_hi_u32 v1, v5, v1
	v_mul_lo_u32 v3, v1, v2
	v_sub_u32_e32 v3, v5, v3
	v_add_u32_e32 v4, 1, v1
	v_cmp_ge_u32_e32 vcc, v3, v2
	s_nop 1
	v_cndmask_b32_e32 v1, v1, v4, vcc
	v_sub_u32_e32 v4, v3, v2
	v_cndmask_b32_e32 v3, v3, v4, vcc
	v_add_u32_e32 v4, 1, v1
	v_cmp_ge_u32_e32 vcc, v3, v2
	v_add_u32_e32 v3, 1, v5
	s_nop 0
	v_cndmask_b32_e32 v1, v1, v4, vcc
	v_mul_lo_u32 v4, v2, v1
	v_add_u32_e32 v2, v4, v2
	v_cmp_ne_u32_e32 vcc, v3, v2
	s_and_saveexec_b64 s[8:9], vcc
	s_xor_b64 s[8:9], exec, s[8:9]
	s_cbranch_execz .LBB0_420
	s_waitcnt lgkmcnt(0)
	v_mov_b32_e32 v0, 0
	s_add_u32 s14, s88, 0xeaf3500
	s_addc_u32 s15, s89, 0
	global_load_dword v0, v0, s[14:15] sc1
	s_waitcnt vmcnt(0)
	v_cmp_eq_u32_e32 vcc, v0, v1
	s_and_saveexec_b64 s[10:11], vcc
	s_cbranch_execz .LBB0_419
	s_add_u32 s12, s88, 0xeaf0200
	s_addc_u32 s13, s89, 0
	s_mov_b32 s2, 1
	s_mov_b64 s[16:17], 0
	v_mov_b32_e32 v0, 0
	s_branch .LBB0_410

.LBB0_1131:
	s_or_b64 exec, exec, s[12:13]
	v_cvt_f32_u32_e32 v4, v2
	s_waitcnt vmcnt(0)
	v_readfirstlane_b32 s2, v3
	v_sub_u32_e32 v3, 0, v2
	v_rcp_iflag_f32_e32 v4, v4
	v_add_u32_e32 v5, s2, v1
	v_mul_f32_e32 v4, 0x4f7ffffe, v4
	v_cvt_u32_f32_e32 v4, v4
	v_mul_lo_u32 v1, v3, v4
	v_mul_hi_u32 v1, v4, v1
	v_add_u32_e32 v1, v4, v1
	v_mul_hi_u32 v1, v5, v1
	v_mul_lo_u32 v3, v1, v2
	v_sub_u32_e32 v3, v5, v3
	v_add_u32_e32 v4, 1, v1
	v_cmp_ge_u32_e32 vcc, v3, v2
	s_nop 1
	v_cndmask_b32_e32 v1, v1, v4, vcc
	v_sub_u32_e32 v4, v3, v2
	v_cndmask_b32_e32 v3, v3, v4, vcc
	v_add_u32_e32 v4, 1, v1
	v_cmp_ge_u32_e32 vcc, v3, v2
	v_add_u32_e32 v3, 1, v5
	s_nop 0
	v_cndmask_b32_e32 v1, v1, v4, vcc
	v_mul_lo_u32 v4, v2, v1
	v_add_u32_e32 v2, v4, v2
	v_cmp_ne_u32_e32 vcc, v3, v2
	s_and_saveexec_b64 s[2:3], vcc
	s_xor_b64 s[10:11], exec, s[2:3]
	s_cbranch_execz .LBB0_1145
	s_waitcnt lgkmcnt(0)
	v_mov_b32_e32 v0, 0
	s_add_u32 s16, s88, 0xeaf3500
	s_addc_u32 s17, s89, 0
	global_load_dword v0, v0, s[16:17] sc1
	s_waitcnt vmcnt(0)
	v_cmp_eq_u32_e32 vcc, v0, v1
	s_and_saveexec_b64 s[12:13], vcc
	s_cbranch_execz .LBB0_1144
	s_add_u32 s14, s88, 0xeaf0200
	s_addc_u32 s15, s89, 0
	s_mov_b32 s2, 1
	s_mov_b64 s[18:19], 0
	v_mov_b32_e32 v0, 0
	s_branch .LBB0_1135
